# prompt RWKV chains get the same per-chunk prefetch-address simplification (lane parts precomputed once per chain, scalar token offset per chunk)
# baseline (speedup 1.0000x reference)
.LBB0_1220:
	s_or_b64 exec, exec, s[6:7]
	v_ashrrev_i32_e32 v63, 6, v5
	v_lshlrev_b32_e32 v42, 3, v63
	s_waitcnt vmcnt(4)
	v_add_u32_e32 v6, s41, v42
	v_bfe_u32 v43, v5, 3, 3
	v_or_b32_e32 v50, v6, v43
	v_lshlrev_b32_e32 v6, 4, v5
	v_lshl_add_u64 v[2:3], v[2:3], 0, s[82:83]
	v_and_b32_e32 v106, 0xf0, v6
	v_lshl_add_u64 v[52:53], v[2:3], 0, v[106:107]
	v_lshlrev_b32_e32 v2, 3, v5
	v_and_b32_e32 v64, 7, v5
	s_waitcnt vmcnt(1)
	v_bfe_u32 v26, v5, 3, 1
	v_and_b32_e32 v5, 56, v2
	v_ashrrev_i32_e32 v51, 31, v50
	s_setprio 2
	v_sub_u32_e32 v2, 0xff, v63
	v_cndmask_b32_e64 v2, v2, v63, s[0:1]
	v_add_u32_e32 v2, s2, v2
	v_ashrrev_i32_e32 v3, 31, v2
	v_lshlrev_b64 v[2:3], 10, v[2:3]
	v_lshl_add_u64 v[2:3], v[52:53], 0, v[2:3]
	global_load_dwordx4 v[6:9], v[2:3], off
	v_add_u32_e32 v2, 4, v63
	v_sub_u32_e32 v3, 0xfb, v63
	v_cndmask_b32_e64 v2, v3, v2, s[0:1]
	v_add_u32_e32 v2, s2, v2
	v_ashrrev_i32_e32 v3, 31, v2
	v_lshlrev_b64 v[2:3], 10, v[2:3]
	v_lshl_add_u64 v[2:3], v[52:53], 0, v[2:3]
	global_load_dwordx4 v[10:13], v[2:3], off
	v_add_u32_e32 v2, 8, v63
	v_sub_u32_e32 v3, 0xf7, v63
	v_cndmask_b32_e64 v2, v3, v2, s[0:1]
	v_add_u32_e32 v2, s2, v2
	v_ashrrev_i32_e32 v3, 31, v2
	v_lshlrev_b64 v[2:3], 10, v[2:3]
	v_lshl_add_u64 v[2:3], v[52:53], 0, v[2:3]
	global_load_dwordx4 v[14:17], v[2:3], off
	v_add_u32_e32 v2, 12, v63
	v_sub_u32_e32 v3, 0xf3, v63
	v_cndmask_b32_e64 v2, v3, v2, s[0:1]
	v_add_u32_e32 v2, s2, v2
	v_ashrrev_i32_e32 v3, 31, v2
	v_lshlrev_b64 v[2:3], 10, v[2:3]
	v_lshl_add_u64 v[2:3], v[52:53], 0, v[2:3]
	global_load_dwordx4 v[18:21], v[2:3], off
	v_lshlrev_b32_e32 v2, 10, v26
	v_mov_b32_e32 v3, v107
	v_lshl_add_u64 v[2:3], s[10:11], 0, v[2:3]
	v_lshlrev_b32_e32 v22, 1, v5
	v_mov_b32_e32 v23, v107
	v_lshl_add_u64 v[54:55], v[2:3], 0, v[22:23]
	v_sub_u32_e32 v2, 0xff, v1
	v_cndmask_b32_e64 v2, v2, v1, s[0:1]
	v_add_u32_e32 v2, s2, v2
	v_mad_i64_i32 v[2:3], s[6:7], v2, s37, v[54:55]
	global_load_dwordx4 v[22:25], v[2:3], off
	v_lshl_or_b32 v2, v4, 8, v106
	s_movk_i32 s4, 0x600
	v_mad_u64_u32 v[56:57], s[6:7], v63, s4, v[2:3]
	v_mul_lo_u32 v2, v1, s4
	v_lshlrev_b32_e32 v3, 8, v26
	v_lshlrev_b32_e32 v4, 2, v5
	v_or3_b32 v57, v2, v3, v4
	v_add_u32_e32 v30, 40, v63
	v_sub_u32_e32 v31, 0xd7, v63
	v_add_u32_e32 v34, 44, v63
	v_sub_u32_e32 v35, 0xd3, v63
	v_cndmask_b32_e64 v30, v31, v30, s[0:1]
	v_cndmask_b32_e64 v34, v35, v34, s[0:1]
	v_add_u32_e32 v30, s2, v30
	v_add_u32_e32 v34, s2, v34
	s_waitcnt vmcnt(5)
	v_sub_u32_e32 v38, 0xdf, v1
	v_add_u32_e32 v39, 32, v1
	v_ashrrev_i32_e32 v31, 31, v30
	v_ashrrev_i32_e32 v35, 31, v34
	v_cndmask_b32_e64 v38, v38, v39, s[0:1]
	v_lshlrev_b64 v[30:31], 10, v[30:31]
	v_lshlrev_b64 v[34:35], 10, v[34:35]
	v_add_u32_e32 v38, s2, v38
	v_lshl_add_u64 v[30:31], v[52:53], 0, v[30:31]
	v_lshl_add_u64 v[34:35], v[52:53], 0, v[34:35]
	v_mad_i64_i32 v[38:39], s[6:7], v38, s37, v[54:55]
	v_add_u32_e32 v42, s38, v42
	v_lshlrev_b32_e32 v65, 4, v64
	v_add_lshl_u32 v42, v42, v43, 2
	v_mov_b32_e32 v106, v107
	v_lshl_add_u64 v[58:59], v[50:51], 2, s[54:55]
	v_lshlrev_b32_e32 v51, 2, v64
	v_lshlrev_b32_e32 v66, 2, v50
	v_or_b32_e32 v67, 0x6000, v65
	v_or_b32_e32 v68, 0x6100, v65
	v_or_b32_e32 v69, 0x6200, v65
	v_or_b32_e32 v70, 0x6300, v65
	v_or_b32_e32 v71, 0x6400, v65
	v_or_b32_e32 v72, 0x6080, v65
	v_or_b32_e32 v73, 0x6180, v65
	v_or_b32_e32 v74, 0x6280, v65
	v_or_b32_e32 v75, 0x6380, v65
	v_or_b32_e32 v76, 0x6480, v65
	v_mul_u32_u24_e32 v77, 0x600, v64
	v_mad_u32_u24 v78, v64, s4, v151
	v_mad_u32_u24 v79, v64, s4, v152
	v_mad_u32_u24 v80, v64, s4, s4
	v_add_u32_e32 v81, 0xb00, v42
	s_mov_b32 s42, 0
	v_sub_u32_e32 v82, 0, v64
	v_add_u32_e32 v83, 0x6b00, v42
	v_or_b32_e32 v84, 0x6600, v65
	v_mov_b64_e32 v[44:45], v[106:107]
	v_mov_b64_e32 v[42:43], v[106:107]
	v_mov_b64_e32 v[48:49], v[106:107]
	v_mov_b64_e32 v[46:47], v[106:107]
	s_waitcnt vmcnt(4)
	ds_write_b128 v56, v[6:9]
	s_waitcnt vmcnt(3)
	ds_write_b128 v56, v[10:13] offset:6144
	s_waitcnt vmcnt(2)
	ds_write_b128 v56, v[14:17] offset:12288
	s_waitcnt vmcnt(1)
	ds_write_b128 v56, v[18:21] offset:18432
	v_add_u32_e32 v10, 24, v63
	v_sub_u32_e32 v11, 0xe7, v63
	v_add_u32_e32 v14, 28, v63
	v_sub_u32_e32 v15, 0xe3, v63
	v_cndmask_b32_e64 v10, v11, v10, s[0:1]
	v_cndmask_b32_e64 v14, v15, v14, s[0:1]
	v_add_u32_e32 v10, s2, v10
	v_add_u32_e32 v14, s2, v14
	v_ashrrev_i32_e32 v11, 31, v10
	v_ashrrev_i32_e32 v15, 31, v14
	v_lshlrev_b64 v[10:11], 10, v[10:11]
	v_lshlrev_b64 v[14:15], 10, v[14:15]
	v_lshl_add_u64 v[10:11], v[52:53], 0, v[10:11]
	v_lshl_add_u64 v[14:15], v[52:53], 0, v[14:15]
	global_load_dwordx4 v[10:13], v[10:11], off
	s_waitcnt vmcnt(1)
	v_lshlrev_b32_e32 v2, 16, v22
	global_load_dwordx4 v[18:21], v[14:15], off
	v_sub_u32_e32 v14, 0xef, v1
	v_add_u32_e32 v15, 16, v1
	v_cndmask_b32_e64 v14, v14, v15, s[0:1]
	v_and_b32_e32 v3, 0xffff0000, v22
	v_lshlrev_b32_e32 v4, 16, v23
	v_and_b32_e32 v5, 0xffff0000, v23
	v_add_u32_e32 v14, s2, v14
	ds_write_b128 v57, v[2:5] offset:1024
	v_lshlrev_b32_e32 v2, 16, v24
	v_and_b32_e32 v3, 0xffff0000, v24
	v_lshlrev_b32_e32 v4, 16, v25
	v_and_b32_e32 v5, 0xffff0000, v25
	v_mad_i64_i32 v[14:15], s[6:7], v14, s37, v[54:55]
	ds_write_b128 v57, v[2:5] offset:1040
	v_add_u32_e32 v2, 16, v63
	v_sub_u32_e32 v3, 0xef, v63
	v_add_u32_e32 v6, 20, v63
	v_sub_u32_e32 v7, 0xeb, v63
	global_load_dwordx4 v[26:29], v[14:15], off
	v_add_u32_e32 v14, 32, v63
	v_sub_u32_e32 v15, 0xdf, v63
	v_add_u32_e32 v22, 36, v63
	v_sub_u32_e32 v23, 0xdb, v63
	v_cndmask_b32_e64 v2, v3, v2, s[0:1]
	v_cndmask_b32_e64 v6, v7, v6, s[0:1]
	v_cndmask_b32_e64 v14, v15, v14, s[0:1]
	v_cndmask_b32_e64 v22, v23, v22, s[0:1]
	v_add_u32_e32 v2, s2, v2
	v_add_u32_e32 v6, s2, v6
	v_add_u32_e32 v14, s2, v14
	v_add_u32_e32 v22, s2, v22
	v_ashrrev_i32_e32 v3, 31, v2
	v_ashrrev_i32_e32 v7, 31, v6
	v_ashrrev_i32_e32 v15, 31, v14
	v_ashrrev_i32_e32 v23, 31, v22
	v_lshlrev_b64 v[2:3], 10, v[2:3]
	v_lshlrev_b64 v[6:7], 10, v[6:7]
	v_lshlrev_b64 v[14:15], 10, v[14:15]
	v_lshlrev_b64 v[22:23], 10, v[22:23]
	v_lshl_add_u64 v[2:3], v[52:53], 0, v[2:3]
	v_lshl_add_u64 v[6:7], v[52:53], 0, v[6:7]
	v_lshl_add_u64 v[14:15], v[52:53], 0, v[14:15]
	v_lshl_add_u64 v[22:23], v[52:53], 0, v[22:23]
	global_load_dwordx4 v[2:5], v[2:3], off
	v_cmp_eq_u32_e64 s[6:7], 7, v64
	global_load_dwordx4 v[6:9], v[6:7], off
	s_nop 0
	global_load_dwordx4 v[14:17], v[14:15], off
	s_nop 0
	global_load_dwordx4 v[22:25], v[22:23], off
	s_nop 0
	global_load_dwordx4 v[30:33], v[30:31], off
	s_nop 0
	global_load_dwordx4 v[34:37], v[34:35], off
	s_nop 0
	global_load_dwordx4 v[38:41], v[38:39], off
	v_lshlrev_b32_e32 v226, 10, v63
	v_sub_u32_e32 v227, 0, v226
	v_cndmask_b32_e64 v228, v227, v226, s[0:1]
	v_ashrrev_i32_e32 v229, 31, v228
	v_lshl_add_u64 v[216:217], v[52:53], 0, v[228:229]
	v_add_u32_e32 v230, 0x1000, v226
	v_sub_u32_e32 v227, 0, v230
	v_cndmask_b32_e64 v228, v227, v230, s[0:1]
	v_ashrrev_i32_e32 v229, 31, v228
	v_lshl_add_u64 v[218:219], v[52:53], 0, v[228:229]
	v_add_u32_e32 v230, 0x2000, v226
	v_sub_u32_e32 v227, 0, v230
	v_cndmask_b32_e64 v228, v227, v230, s[0:1]
	v_ashrrev_i32_e32 v229, 31, v228
	v_lshl_add_u64 v[220:221], v[52:53], 0, v[228:229]
	v_add_u32_e32 v230, 0x3000, v226
	v_sub_u32_e32 v227, 0, v230
	v_cndmask_b32_e64 v228, v227, v230, s[0:1]
	v_ashrrev_i32_e32 v229, 31, v228
	v_lshl_add_u64 v[222:223], v[52:53], 0, v[228:229]
	v_mul_lo_u32 v230, v1, s37
	v_sub_u32_e32 v227, 0, v230
	v_cndmask_b32_e64 v228, v227, v230, s[0:1]
	v_ashrrev_i32_e32 v229, 31, v228
	v_lshl_add_u64 v[224:225], v[54:55], 0, v[228:229]
	s_waitcnt lgkmcnt(0)
	s_barrier
	s_branch .LBB0_1222

.LBB0_1222:
	ds_read_b128 v[156:159], v65 offset:0
	ds_read_b128 v[160:163], v65 offset:128
	ds_read_b128 v[164:167], v65 offset:256
	ds_read_b128 v[168:171], v65 offset:384
	ds_read_b128 v[172:175], v65 offset:768
	ds_read_b128 v[176:179], v65 offset:896
	ds_read_b32 v196, v66 offset:1280
	ds_read_b128 v[180:183], v65 offset:512
	ds_read_b128 v[184:187], v65 offset:640
	ds_read_b128 v[188:191], v65 offset:1024
	ds_read_b128 v[192:195], v65 offset:1152
	s_waitcnt lgkmcnt(2)
	v_pk_mul_f32 v[72:73], v[46:47], v[156:157]
	v_pk_mul_f32 v[74:75], v[46:47], v[164:165]
	v_pk_fma_f32 v[72:73], v[48:49], v[158:159], v[72:73]
	v_pk_mul_f32 v[76:77], v[48:49], v[166:167]
	v_pk_fma_f32 v[72:73], v[42:43], v[160:161], v[72:73]
	v_pk_mul_f32 v[78:79], v[42:43], v[168:169]
	v_pk_fma_f32 v[72:73], v[44:45], v[162:163], v[72:73]
	v_pk_mul_f32 v[80:81], v[44:45], v[170:171]
	v_add_f32_e32 v82, v72, v73
	ds_read_b128 v[114:117], v65 offset:1536
	v_pk_fma_f32 v[74:75], v[196:197], v[172:173], v[74:75] op_sel_hi:[0,1,1]
	v_add_f32_dpp v82, v82, v82 quad_perm:[1,0,3,2] row_mask:0xf bank_mask:0xf bound_ctrl:1
	ds_read_b128 v[118:121], v65 offset:1664
	v_pk_fma_f32 v[76:77], v[196:197], v[174:175], v[76:77] op_sel_hi:[0,1,1]
	v_add_f32_dpp v82, v82, v82 quad_perm:[2,3,0,1] row_mask:0xf bank_mask:0xf bound_ctrl:1
	ds_read_b128 v[122:125], v65 offset:1792
	v_pk_fma_f32 v[78:79], v[196:197], v[176:177], v[78:79] op_sel_hi:[0,1,1]
	v_add_f32_dpp v82, v82, v82 row_half_mirror row_mask:0xf bank_mask:0xf bound_ctrl:1
	v_pk_fma_f32 v[80:81], v[196:197], v[178:179], v[80:81] op_sel_hi:[0,1,1]
	ds_read_b128 v[126:129], v65 offset:1920
	v_pk_fma_f32 v[46:47], v[180:181], v[82:83], v[74:75] op_sel_hi:[1,0,1]
	ds_read_b128 v[108:111], v65 offset:2304
	v_pk_fma_f32 v[48:49], v[182:183], v[82:83], v[76:77] op_sel_hi:[1,0,1]
	ds_read_b128 v[88:91], v65 offset:2432
	v_pk_fma_f32 v[42:43], v[184:185], v[82:83], v[78:79] op_sel_hi:[1,0,1]
	ds_read_b32 v198, v66 offset:2816
	v_pk_fma_f32 v[44:45], v[186:187], v[82:83], v[80:81] op_sel_hi:[1,0,1]
	ds_read_b128 v[92:95], v65 offset:2048
	ds_read_b128 v[96:99], v65 offset:2176
	ds_read_b128 v[100:103], v65 offset:2560
	ds_read_b128 v[68:71], v65 offset:2688
	s_waitcnt lgkmcnt(2)
	v_pk_mul_f32 v[72:73], v[46:47], v[114:115]
	v_pk_mul_f32 v[84:85], v[46:47], v[188:189]
	v_pk_fma_f32 v[72:73], v[48:49], v[116:117], v[72:73]
	v_pk_fma_f32 v[84:85], v[48:49], v[190:191], v[84:85]
	v_pk_fma_f32 v[72:73], v[42:43], v[118:119], v[72:73]
	v_pk_fma_f32 v[84:85], v[42:43], v[192:193], v[84:85]
	v_pk_fma_f32 v[72:73], v[44:45], v[120:121], v[72:73]
	v_pk_fma_f32 v[84:85], v[44:45], v[194:195], v[84:85]
	v_add_f32_e32 v82, v72, v73
	v_add_f32_e32 v83, v84, v85
	ds_read_b128 v[156:159], v65 offset:3072
	v_pk_mul_f32 v[74:75], v[46:47], v[122:123]
	v_add_f32_dpp v82, v82, v82 quad_perm:[1,0,3,2] row_mask:0xf bank_mask:0xf bound_ctrl:1
	ds_read_b128 v[160:163], v65 offset:3200
	v_pk_mul_f32 v[76:77], v[48:49], v[124:125]
	v_add_f32_dpp v82, v82, v82 quad_perm:[2,3,0,1] row_mask:0xf bank_mask:0xf bound_ctrl:1
	ds_read_b128 v[164:167], v65 offset:3328
	v_pk_mul_f32 v[78:79], v[42:43], v[126:127]
	v_add_f32_dpp v82, v82, v82 row_half_mirror row_mask:0xf bank_mask:0xf bound_ctrl:1
	v_pk_mul_f32 v[80:81], v[44:45], v[128:129]
	ds_read_b128 v[168:171], v65 offset:3456
	v_pk_fma_f32 v[74:75], v[198:199], v[108:109], v[74:75] op_sel_hi:[0,1,1]
	ds_read_b128 v[172:175], v65 offset:3840
	v_pk_fma_f32 v[76:77], v[198:199], v[110:111], v[76:77] op_sel_hi:[0,1,1]
	ds_read_b128 v[176:179], v65 offset:3968
	v_pk_fma_f32 v[78:79], v[198:199], v[88:89], v[78:79] op_sel_hi:[0,1,1]
	ds_read_b32 v196, v66 offset:4352
	v_pk_fma_f32 v[80:81], v[198:199], v[90:91], v[80:81] op_sel_hi:[0,1,1]
	ds_read_b128 v[180:183], v65 offset:3584
	v_pk_fma_f32 v[46:47], v[92:93], v[82:83], v[74:75] op_sel_hi:[1,0,1]
	ds_read_b128 v[184:187], v65 offset:3712
	v_pk_fma_f32 v[48:49], v[94:95], v[82:83], v[76:77] op_sel_hi:[1,0,1]
	ds_read_b128 v[188:191], v65 offset:4096
	v_pk_fma_f32 v[42:43], v[96:97], v[82:83], v[78:79] op_sel_hi:[1,0,1]
	ds_read_b128 v[192:195], v65 offset:4224
	v_pk_fma_f32 v[44:45], v[98:99], v[82:83], v[80:81] op_sel_hi:[1,0,1]
	s_waitcnt lgkmcnt(2)
	v_pk_mul_f32 v[72:73], v[46:47], v[156:157]
	v_pk_mul_f32 v[84:85], v[46:47], v[100:101]
	v_pk_fma_f32 v[72:73], v[48:49], v[158:159], v[72:73]
	v_pk_fma_f32 v[84:85], v[48:49], v[102:103], v[84:85]
	v_pk_fma_f32 v[72:73], v[42:43], v[160:161], v[72:73]
	v_pk_fma_f32 v[84:85], v[42:43], v[68:69], v[84:85]
	v_pk_fma_f32 v[72:73], v[44:45], v[162:163], v[72:73]
	v_pk_fma_f32 v[84:85], v[44:45], v[70:71], v[84:85]
	v_add_f32_e32 v82, v72, v73
	v_add_f32_e32 v87, v84, v85
	ds_read_b128 v[114:117], v65 offset:4608
	v_pk_mul_f32 v[74:75], v[46:47], v[164:165]
	v_add_f32_dpp v82, v82, v82 quad_perm:[1,0,3,2] row_mask:0xf bank_mask:0xf bound_ctrl:1
	ds_read_b128 v[118:121], v65 offset:4736
	v_pk_mul_f32 v[76:77], v[48:49], v[166:167]
	v_add_f32_dpp v82, v82, v82 quad_perm:[2,3,0,1] row_mask:0xf bank_mask:0xf bound_ctrl:1
	ds_read_b128 v[122:125], v65 offset:4864
	v_pk_mul_f32 v[78:79], v[42:43], v[168:169]
	v_add_f32_dpp v82, v82, v82 row_half_mirror row_mask:0xf bank_mask:0xf bound_ctrl:1
	v_pk_mul_f32 v[80:81], v[44:45], v[170:171]
	ds_read_b128 v[126:129], v65 offset:4992
	v_pk_fma_f32 v[74:75], v[196:197], v[172:173], v[74:75] op_sel_hi:[0,1,1]
	ds_read_b128 v[108:111], v65 offset:5376
	v_pk_fma_f32 v[76:77], v[196:197], v[174:175], v[76:77] op_sel_hi:[0,1,1]
	ds_read_b128 v[88:91], v65 offset:5504
	v_pk_fma_f32 v[78:79], v[196:197], v[176:177], v[78:79] op_sel_hi:[0,1,1]
	ds_read_b32 v198, v66 offset:5888
	v_pk_fma_f32 v[80:81], v[196:197], v[178:179], v[80:81] op_sel_hi:[0,1,1]
	ds_read_b128 v[92:95], v65 offset:5120
	v_pk_fma_f32 v[46:47], v[180:181], v[82:83], v[74:75] op_sel_hi:[1,0,1]
	ds_read_b128 v[96:99], v65 offset:5248
	v_pk_fma_f32 v[48:49], v[182:183], v[82:83], v[76:77] op_sel_hi:[1,0,1]
	ds_read_b128 v[100:103], v65 offset:5632
	v_pk_fma_f32 v[42:43], v[184:185], v[82:83], v[78:79] op_sel_hi:[1,0,1]
	ds_read_b128 v[68:71], v65 offset:5760
	v_pk_fma_f32 v[44:45], v[186:187], v[82:83], v[80:81] op_sel_hi:[1,0,1]
	s_waitcnt lgkmcnt(2)
	v_pk_mul_f32 v[72:73], v[46:47], v[114:115]
	v_pk_mul_f32 v[84:85], v[46:47], v[188:189]
	v_pk_fma_f32 v[72:73], v[48:49], v[116:117], v[72:73]
	v_pk_fma_f32 v[84:85], v[48:49], v[190:191], v[84:85]
	v_pk_fma_f32 v[72:73], v[42:43], v[118:119], v[72:73]
	v_pk_fma_f32 v[84:85], v[42:43], v[192:193], v[84:85]
	v_pk_fma_f32 v[72:73], v[44:45], v[120:121], v[72:73]
	v_pk_fma_f32 v[84:85], v[44:45], v[194:195], v[84:85]
	v_add_f32_e32 v82, v72, v73
	v_add_f32_e32 v104, v84, v85
	ds_read_b128 v[156:159], v65 offset:6144
	v_pk_mul_f32 v[74:75], v[46:47], v[122:123]
	v_add_f32_dpp v82, v82, v82 quad_perm:[1,0,3,2] row_mask:0xf bank_mask:0xf bound_ctrl:1
	ds_read_b128 v[160:163], v65 offset:6272
	v_pk_mul_f32 v[76:77], v[48:49], v[124:125]
	v_add_f32_dpp v82, v82, v82 quad_perm:[2,3,0,1] row_mask:0xf bank_mask:0xf bound_ctrl:1
	ds_read_b128 v[164:167], v65 offset:6400
	v_pk_mul_f32 v[78:79], v[42:43], v[126:127]
	v_add_f32_dpp v82, v82, v82 row_half_mirror row_mask:0xf bank_mask:0xf bound_ctrl:1
	v_pk_mul_f32 v[80:81], v[44:45], v[128:129]
	ds_read_b128 v[168:171], v65 offset:6528
	v_pk_fma_f32 v[74:75], v[198:199], v[108:109], v[74:75] op_sel_hi:[0,1,1]
	ds_read_b128 v[172:175], v65 offset:6912
	v_pk_fma_f32 v[76:77], v[198:199], v[110:111], v[76:77] op_sel_hi:[0,1,1]
	ds_read_b128 v[176:179], v65 offset:7040
	v_pk_fma_f32 v[78:79], v[198:199], v[88:89], v[78:79] op_sel_hi:[0,1,1]
	ds_read_b32 v196, v66 offset:7424
	v_pk_fma_f32 v[80:81], v[198:199], v[90:91], v[80:81] op_sel_hi:[0,1,1]
	ds_read_b128 v[180:183], v65 offset:6656
	v_pk_fma_f32 v[46:47], v[92:93], v[82:83], v[74:75] op_sel_hi:[1,0,1]
	ds_read_b128 v[184:187], v65 offset:6784
	v_pk_fma_f32 v[48:49], v[94:95], v[82:83], v[76:77] op_sel_hi:[1,0,1]
	ds_read_b128 v[188:191], v65 offset:7168
	v_pk_fma_f32 v[42:43], v[96:97], v[82:83], v[78:79] op_sel_hi:[1,0,1]
	ds_read_b128 v[192:195], v65 offset:7296
	v_pk_fma_f32 v[44:45], v[98:99], v[82:83], v[80:81] op_sel_hi:[1,0,1]
	s_waitcnt lgkmcnt(2)
	v_pk_mul_f32 v[72:73], v[46:47], v[156:157]
	v_pk_mul_f32 v[84:85], v[46:47], v[100:101]
	v_pk_fma_f32 v[72:73], v[48:49], v[158:159], v[72:73]
	v_pk_fma_f32 v[84:85], v[48:49], v[102:103], v[84:85]
	v_pk_fma_f32 v[72:73], v[42:43], v[160:161], v[72:73]
	v_pk_fma_f32 v[84:85], v[42:43], v[68:69], v[84:85]
	v_pk_fma_f32 v[72:73], v[44:45], v[162:163], v[72:73]
	v_pk_fma_f32 v[84:85], v[44:45], v[70:71], v[84:85]
	v_add_f32_e32 v82, v72, v73
	v_add_f32_e32 v105, v84, v85
	ds_read_b128 v[114:117], v65 offset:7680
	v_pk_mul_f32 v[74:75], v[46:47], v[164:165]
	v_add_f32_dpp v82, v82, v82 quad_perm:[1,0,3,2] row_mask:0xf bank_mask:0xf bound_ctrl:1
	ds_read_b128 v[118:121], v65 offset:7808
	v_pk_mul_f32 v[76:77], v[48:49], v[166:167]
	v_add_f32_dpp v82, v82, v82 quad_perm:[2,3,0,1] row_mask:0xf bank_mask:0xf bound_ctrl:1
	ds_read_b128 v[122:125], v65 offset:7936
	v_pk_mul_f32 v[78:79], v[42:43], v[168:169]
	v_add_f32_dpp v82, v82, v82 row_half_mirror row_mask:0xf bank_mask:0xf bound_ctrl:1
	v_pk_mul_f32 v[80:81], v[44:45], v[170:171]
	ds_read_b128 v[126:129], v65 offset:8064
	v_pk_fma_f32 v[74:75], v[196:197], v[172:173], v[74:75] op_sel_hi:[0,1,1]
	ds_read_b128 v[108:111], v65 offset:8448
	v_pk_fma_f32 v[76:77], v[196:197], v[174:175], v[76:77] op_sel_hi:[0,1,1]
	ds_read_b128 v[88:91], v65 offset:8576
	v_pk_fma_f32 v[78:79], v[196:197], v[176:177], v[78:79] op_sel_hi:[0,1,1]
	ds_read_b32 v198, v66 offset:8960
	v_pk_fma_f32 v[80:81], v[196:197], v[178:179], v[80:81] op_sel_hi:[0,1,1]
	ds_read_b128 v[92:95], v65 offset:8192
	v_pk_fma_f32 v[46:47], v[180:181], v[82:83], v[74:75] op_sel_hi:[1,0,1]
	ds_read_b128 v[96:99], v65 offset:8320
	v_pk_fma_f32 v[48:49], v[182:183], v[82:83], v[76:77] op_sel_hi:[1,0,1]
	ds_read_b128 v[100:103], v65 offset:8704
	v_pk_fma_f32 v[42:43], v[184:185], v[82:83], v[78:79] op_sel_hi:[1,0,1]
	ds_read_b128 v[68:71], v65 offset:8832
	v_pk_fma_f32 v[44:45], v[186:187], v[82:83], v[80:81] op_sel_hi:[1,0,1]
	s_waitcnt lgkmcnt(2)
	v_pk_mul_f32 v[72:73], v[46:47], v[114:115]
	v_pk_mul_f32 v[84:85], v[46:47], v[188:189]
	v_pk_fma_f32 v[72:73], v[48:49], v[116:117], v[72:73]
	v_pk_fma_f32 v[84:85], v[48:49], v[190:191], v[84:85]
	v_pk_fma_f32 v[72:73], v[42:43], v[118:119], v[72:73]
	v_pk_fma_f32 v[84:85], v[42:43], v[192:193], v[84:85]
	v_pk_fma_f32 v[72:73], v[44:45], v[120:121], v[72:73]
	v_pk_fma_f32 v[84:85], v[44:45], v[194:195], v[84:85]
	v_add_f32_e32 v82, v72, v73
	v_add_f32_e32 v67, v84, v85
	ds_read_b128 v[156:159], v65 offset:9216
	v_pk_mul_f32 v[74:75], v[46:47], v[122:123]
	v_add_f32_dpp v82, v82, v82 quad_perm:[1,0,3,2] row_mask:0xf bank_mask:0xf bound_ctrl:1
	ds_read_b128 v[160:163], v65 offset:9344
	v_pk_mul_f32 v[76:77], v[48:49], v[124:125]
	v_add_f32_dpp v82, v82, v82 quad_perm:[2,3,0,1] row_mask:0xf bank_mask:0xf bound_ctrl:1
	ds_read_b128 v[164:167], v65 offset:9472
	v_pk_mul_f32 v[78:79], v[42:43], v[126:127]
	v_add_f32_dpp v82, v82, v82 row_half_mirror row_mask:0xf bank_mask:0xf bound_ctrl:1
	v_pk_mul_f32 v[80:81], v[44:45], v[128:129]
	ds_read_b128 v[168:171], v65 offset:9600
	v_pk_fma_f32 v[74:75], v[198:199], v[108:109], v[74:75] op_sel_hi:[0,1,1]
	ds_read_b128 v[172:175], v65 offset:9984
	v_pk_fma_f32 v[76:77], v[198:199], v[110:111], v[76:77] op_sel_hi:[0,1,1]
	ds_read_b128 v[176:179], v65 offset:10112
	v_pk_fma_f32 v[78:79], v[198:199], v[88:89], v[78:79] op_sel_hi:[0,1,1]
	ds_read_b32 v196, v66 offset:10496
	v_pk_fma_f32 v[80:81], v[198:199], v[90:91], v[80:81] op_sel_hi:[0,1,1]
	ds_read_b128 v[180:183], v65 offset:9728
	v_pk_fma_f32 v[46:47], v[92:93], v[82:83], v[74:75] op_sel_hi:[1,0,1]
	ds_read_b128 v[184:187], v65 offset:9856
	v_pk_fma_f32 v[48:49], v[94:95], v[82:83], v[76:77] op_sel_hi:[1,0,1]
	ds_read_b128 v[188:191], v65 offset:10240
	v_pk_fma_f32 v[42:43], v[96:97], v[82:83], v[78:79] op_sel_hi:[1,0,1]
	ds_read_b128 v[192:195], v65 offset:10368
	v_pk_fma_f32 v[44:45], v[98:99], v[82:83], v[80:81] op_sel_hi:[1,0,1]
	s_waitcnt lgkmcnt(2)
	v_pk_mul_f32 v[72:73], v[46:47], v[156:157]
	v_pk_mul_f32 v[84:85], v[46:47], v[100:101]
	v_pk_fma_f32 v[72:73], v[48:49], v[158:159], v[72:73]
	v_pk_fma_f32 v[84:85], v[48:49], v[102:103], v[84:85]
	v_pk_fma_f32 v[72:73], v[42:43], v[160:161], v[72:73]
	v_pk_fma_f32 v[84:85], v[42:43], v[68:69], v[84:85]
	v_pk_fma_f32 v[72:73], v[44:45], v[162:163], v[72:73]
	v_pk_fma_f32 v[84:85], v[44:45], v[70:71], v[84:85]
	v_add_f32_e32 v82, v72, v73
	v_add_f32_e32 v60, v84, v85
	ds_read_b128 v[114:117], v65 offset:10752
	v_pk_mul_f32 v[74:75], v[46:47], v[164:165]
	v_add_f32_dpp v82, v82, v82 quad_perm:[1,0,3,2] row_mask:0xf bank_mask:0xf bound_ctrl:1
	ds_read_b128 v[118:121], v65 offset:10880
	v_pk_mul_f32 v[76:77], v[48:49], v[166:167]
	v_add_f32_dpp v82, v82, v82 quad_perm:[2,3,0,1] row_mask:0xf bank_mask:0xf bound_ctrl:1
	ds_read_b128 v[122:125], v65 offset:11008
	v_pk_mul_f32 v[78:79], v[42:43], v[168:169]
	v_add_f32_dpp v82, v82, v82 row_half_mirror row_mask:0xf bank_mask:0xf bound_ctrl:1
	v_pk_mul_f32 v[80:81], v[44:45], v[170:171]
	ds_read_b128 v[126:129], v65 offset:11136
	v_pk_fma_f32 v[74:75], v[196:197], v[172:173], v[74:75] op_sel_hi:[0,1,1]
	ds_read_b128 v[108:111], v65 offset:11520
	v_pk_fma_f32 v[76:77], v[196:197], v[174:175], v[76:77] op_sel_hi:[0,1,1]
	ds_read_b128 v[88:91], v65 offset:11648
	v_pk_fma_f32 v[78:79], v[196:197], v[176:177], v[78:79] op_sel_hi:[0,1,1]
	ds_read_b32 v198, v66 offset:12032
	v_pk_fma_f32 v[80:81], v[196:197], v[178:179], v[80:81] op_sel_hi:[0,1,1]
	ds_read_b128 v[92:95], v65 offset:11264
	v_pk_fma_f32 v[46:47], v[180:181], v[82:83], v[74:75] op_sel_hi:[1,0,1]
	ds_read_b128 v[96:99], v65 offset:11392
	v_pk_fma_f32 v[48:49], v[182:183], v[82:83], v[76:77] op_sel_hi:[1,0,1]
	ds_read_b128 v[100:103], v65 offset:11776
	v_pk_fma_f32 v[42:43], v[184:185], v[82:83], v[78:79] op_sel_hi:[1,0,1]
	ds_read_b128 v[68:71], v65 offset:11904
	v_pk_fma_f32 v[44:45], v[186:187], v[82:83], v[80:81] op_sel_hi:[1,0,1]
	s_waitcnt lgkmcnt(2)
	v_pk_mul_f32 v[72:73], v[46:47], v[114:115]
	v_pk_mul_f32 v[84:85], v[46:47], v[188:189]
	v_pk_fma_f32 v[72:73], v[48:49], v[116:117], v[72:73]
	v_pk_fma_f32 v[84:85], v[48:49], v[190:191], v[84:85]
	v_pk_fma_f32 v[72:73], v[42:43], v[118:119], v[72:73]
	v_pk_fma_f32 v[84:85], v[42:43], v[192:193], v[84:85]
	v_pk_fma_f32 v[72:73], v[44:45], v[120:121], v[72:73]
	v_pk_fma_f32 v[84:85], v[44:45], v[194:195], v[84:85]
	v_add_f32_e32 v82, v72, v73
	v_add_f32_e32 v62, v84, v85
	ds_read_b128 v[156:159], v65 offset:12288
	v_pk_mul_f32 v[74:75], v[46:47], v[122:123]
	v_add_f32_dpp v82, v82, v82 quad_perm:[1,0,3,2] row_mask:0xf bank_mask:0xf bound_ctrl:1
	ds_read_b128 v[160:163], v65 offset:12416
	v_pk_mul_f32 v[76:77], v[48:49], v[124:125]
	v_add_f32_dpp v82, v82, v82 quad_perm:[2,3,0,1] row_mask:0xf bank_mask:0xf bound_ctrl:1
	ds_read_b128 v[164:167], v65 offset:12544
	v_pk_mul_f32 v[78:79], v[42:43], v[126:127]
	v_add_f32_dpp v82, v82, v82 row_half_mirror row_mask:0xf bank_mask:0xf bound_ctrl:1
	v_pk_mul_f32 v[80:81], v[44:45], v[128:129]
	ds_read_b128 v[168:171], v65 offset:12672
	v_pk_fma_f32 v[74:75], v[198:199], v[108:109], v[74:75] op_sel_hi:[0,1,1]
	ds_read_b128 v[172:175], v65 offset:13056
	v_pk_fma_f32 v[76:77], v[198:199], v[110:111], v[76:77] op_sel_hi:[0,1,1]
	ds_read_b128 v[176:179], v65 offset:13184
	v_pk_fma_f32 v[78:79], v[198:199], v[88:89], v[78:79] op_sel_hi:[0,1,1]
	ds_read_b32 v196, v66 offset:13568
	v_pk_fma_f32 v[80:81], v[198:199], v[90:91], v[80:81] op_sel_hi:[0,1,1]
	ds_read_b128 v[180:183], v65 offset:12800
	v_pk_fma_f32 v[46:47], v[92:93], v[82:83], v[74:75] op_sel_hi:[1,0,1]
	ds_read_b128 v[184:187], v65 offset:12928
	v_pk_fma_f32 v[48:49], v[94:95], v[82:83], v[76:77] op_sel_hi:[1,0,1]
	ds_read_b128 v[188:191], v65 offset:13312
	v_pk_fma_f32 v[42:43], v[96:97], v[82:83], v[78:79] op_sel_hi:[1,0,1]
	ds_read_b128 v[192:195], v65 offset:13440
	v_pk_fma_f32 v[44:45], v[98:99], v[82:83], v[80:81] op_sel_hi:[1,0,1]
	s_waitcnt lgkmcnt(2)
	v_pk_mul_f32 v[72:73], v[46:47], v[156:157]
	v_pk_mul_f32 v[84:85], v[46:47], v[100:101]
	v_pk_fma_f32 v[72:73], v[48:49], v[158:159], v[72:73]
	v_pk_fma_f32 v[84:85], v[48:49], v[102:103], v[84:85]
	v_pk_fma_f32 v[72:73], v[42:43], v[160:161], v[72:73]
	v_pk_fma_f32 v[84:85], v[42:43], v[68:69], v[84:85]
	v_pk_fma_f32 v[72:73], v[44:45], v[162:163], v[72:73]
	v_pk_fma_f32 v[84:85], v[44:45], v[70:71], v[84:85]
	v_add_f32_e32 v82, v72, v73
	v_add_f32_e32 v197, v84, v85
	ds_read_b128 v[114:117], v65 offset:13824
	v_pk_mul_f32 v[74:75], v[46:47], v[164:165]
	v_add_f32_dpp v82, v82, v82 quad_perm:[1,0,3,2] row_mask:0xf bank_mask:0xf bound_ctrl:1
	ds_read_b128 v[118:121], v65 offset:13952
	v_pk_mul_f32 v[76:77], v[48:49], v[166:167]
	v_add_f32_dpp v82, v82, v82 quad_perm:[2,3,0,1] row_mask:0xf bank_mask:0xf bound_ctrl:1
	ds_read_b128 v[122:125], v65 offset:14080
	v_pk_mul_f32 v[78:79], v[42:43], v[168:169]
	v_add_f32_dpp v82, v82, v82 row_half_mirror row_mask:0xf bank_mask:0xf bound_ctrl:1
	v_pk_mul_f32 v[80:81], v[44:45], v[170:171]
	ds_read_b128 v[126:129], v65 offset:14208
	v_pk_fma_f32 v[74:75], v[196:197], v[172:173], v[74:75] op_sel_hi:[0,1,1]
	ds_read_b128 v[108:111], v65 offset:14592
	v_pk_fma_f32 v[76:77], v[196:197], v[174:175], v[76:77] op_sel_hi:[0,1,1]
	ds_read_b128 v[88:91], v65 offset:14720
	v_pk_fma_f32 v[78:79], v[196:197], v[176:177], v[78:79] op_sel_hi:[0,1,1]
	ds_read_b32 v198, v66 offset:15104
	v_pk_fma_f32 v[80:81], v[196:197], v[178:179], v[80:81] op_sel_hi:[0,1,1]
	ds_read_b128 v[92:95], v65 offset:14336
	v_pk_fma_f32 v[46:47], v[180:181], v[82:83], v[74:75] op_sel_hi:[1,0,1]
	ds_read_b128 v[96:99], v65 offset:14464
	v_pk_fma_f32 v[48:49], v[182:183], v[82:83], v[76:77] op_sel_hi:[1,0,1]
	ds_read_b128 v[100:103], v65 offset:14848
	v_pk_fma_f32 v[42:43], v[184:185], v[82:83], v[78:79] op_sel_hi:[1,0,1]
	ds_read_b128 v[68:71], v65 offset:14976
	v_pk_fma_f32 v[44:45], v[186:187], v[82:83], v[80:81] op_sel_hi:[1,0,1]
	s_waitcnt lgkmcnt(2)
	v_pk_mul_f32 v[72:73], v[46:47], v[114:115]
	v_pk_mul_f32 v[84:85], v[46:47], v[188:189]
	v_pk_fma_f32 v[72:73], v[48:49], v[116:117], v[72:73]
	v_pk_fma_f32 v[84:85], v[48:49], v[190:191], v[84:85]
	v_pk_fma_f32 v[72:73], v[42:43], v[118:119], v[72:73]
	v_pk_fma_f32 v[84:85], v[42:43], v[192:193], v[84:85]
	v_pk_fma_f32 v[72:73], v[44:45], v[120:121], v[72:73]
	v_pk_fma_f32 v[84:85], v[44:45], v[194:195], v[84:85]
	v_add_f32_e32 v82, v72, v73
	v_add_f32_e32 v199, v84, v85
	ds_read_b128 v[156:159], v65 offset:15360
	v_pk_mul_f32 v[74:75], v[46:47], v[122:123]
	v_add_f32_dpp v82, v82, v82 quad_perm:[1,0,3,2] row_mask:0xf bank_mask:0xf bound_ctrl:1
	ds_read_b128 v[160:163], v65 offset:15488
	v_pk_mul_f32 v[76:77], v[48:49], v[124:125]
	v_add_f32_dpp v82, v82, v82 quad_perm:[2,3,0,1] row_mask:0xf bank_mask:0xf bound_ctrl:1
	ds_read_b128 v[164:167], v65 offset:15616
	v_pk_mul_f32 v[78:79], v[42:43], v[126:127]
	v_add_f32_dpp v82, v82, v82 row_half_mirror row_mask:0xf bank_mask:0xf bound_ctrl:1
	v_pk_mul_f32 v[80:81], v[44:45], v[128:129]
	ds_read_b128 v[168:171], v65 offset:15744
	v_pk_fma_f32 v[74:75], v[198:199], v[108:109], v[74:75] op_sel_hi:[0,1,1]
	ds_read_b128 v[172:175], v65 offset:16128
	v_pk_fma_f32 v[76:77], v[198:199], v[110:111], v[76:77] op_sel_hi:[0,1,1]
	ds_read_b128 v[176:179], v65 offset:16256
	v_pk_fma_f32 v[78:79], v[198:199], v[88:89], v[78:79] op_sel_hi:[0,1,1]
	ds_read_b32 v196, v66 offset:16640
	v_pk_fma_f32 v[80:81], v[198:199], v[90:91], v[80:81] op_sel_hi:[0,1,1]
	ds_read_b128 v[180:183], v65 offset:15872
	v_pk_fma_f32 v[46:47], v[92:93], v[82:83], v[74:75] op_sel_hi:[1,0,1]
	ds_read_b128 v[184:187], v65 offset:16000
	v_pk_fma_f32 v[48:49], v[94:95], v[82:83], v[76:77] op_sel_hi:[1,0,1]
	ds_read_b128 v[188:191], v65 offset:16384
	v_pk_fma_f32 v[42:43], v[96:97], v[82:83], v[78:79] op_sel_hi:[1,0,1]
	ds_read_b128 v[192:195], v65 offset:16512
	v_pk_fma_f32 v[44:45], v[98:99], v[82:83], v[80:81] op_sel_hi:[1,0,1]
	s_waitcnt lgkmcnt(2)
	v_pk_mul_f32 v[72:73], v[46:47], v[156:157]
	v_pk_mul_f32 v[84:85], v[46:47], v[100:101]
	v_pk_fma_f32 v[72:73], v[48:49], v[158:159], v[72:73]
	v_pk_fma_f32 v[84:85], v[48:49], v[102:103], v[84:85]
	v_pk_fma_f32 v[72:73], v[42:43], v[160:161], v[72:73]
	v_pk_fma_f32 v[84:85], v[42:43], v[68:69], v[84:85]
	v_pk_fma_f32 v[72:73], v[44:45], v[162:163], v[72:73]
	v_pk_fma_f32 v[84:85], v[44:45], v[70:71], v[84:85]
	v_add_f32_e32 v82, v72, v73
	v_add_f32_e32 v200, v84, v85
	ds_read_b128 v[114:117], v65 offset:16896
	v_pk_mul_f32 v[74:75], v[46:47], v[164:165]
	v_add_f32_dpp v82, v82, v82 quad_perm:[1,0,3,2] row_mask:0xf bank_mask:0xf bound_ctrl:1
	ds_read_b128 v[118:121], v65 offset:17024
	v_pk_mul_f32 v[76:77], v[48:49], v[166:167]
	v_add_f32_dpp v82, v82, v82 quad_perm:[2,3,0,1] row_mask:0xf bank_mask:0xf bound_ctrl:1
	ds_read_b128 v[122:125], v65 offset:17152
	v_pk_mul_f32 v[78:79], v[42:43], v[168:169]
	v_add_f32_dpp v82, v82, v82 row_half_mirror row_mask:0xf bank_mask:0xf bound_ctrl:1
	v_pk_mul_f32 v[80:81], v[44:45], v[170:171]
	ds_read_b128 v[126:129], v65 offset:17280
	v_pk_fma_f32 v[74:75], v[196:197], v[172:173], v[74:75] op_sel_hi:[0,1,1]
	ds_read_b128 v[108:111], v65 offset:17664
	v_pk_fma_f32 v[76:77], v[196:197], v[174:175], v[76:77] op_sel_hi:[0,1,1]
	ds_read_b128 v[88:91], v65 offset:17792
	v_pk_fma_f32 v[78:79], v[196:197], v[176:177], v[78:79] op_sel_hi:[0,1,1]
	ds_read_b32 v198, v66 offset:18176
	v_pk_fma_f32 v[80:81], v[196:197], v[178:179], v[80:81] op_sel_hi:[0,1,1]
	ds_read_b128 v[92:95], v65 offset:17408
	v_pk_fma_f32 v[46:47], v[180:181], v[82:83], v[74:75] op_sel_hi:[1,0,1]
	ds_read_b128 v[96:99], v65 offset:17536
	v_pk_fma_f32 v[48:49], v[182:183], v[82:83], v[76:77] op_sel_hi:[1,0,1]
	ds_read_b128 v[100:103], v65 offset:17920
	v_pk_fma_f32 v[42:43], v[184:185], v[82:83], v[78:79] op_sel_hi:[1,0,1]
	ds_read_b128 v[68:71], v65 offset:18048
	v_pk_fma_f32 v[44:45], v[186:187], v[82:83], v[80:81] op_sel_hi:[1,0,1]
	s_waitcnt lgkmcnt(2)
	v_pk_mul_f32 v[72:73], v[46:47], v[114:115]
	v_pk_mul_f32 v[84:85], v[46:47], v[188:189]
	v_pk_fma_f32 v[72:73], v[48:49], v[116:117], v[72:73]
	v_pk_fma_f32 v[84:85], v[48:49], v[190:191], v[84:85]
	v_pk_fma_f32 v[72:73], v[42:43], v[118:119], v[72:73]
	v_pk_fma_f32 v[84:85], v[42:43], v[192:193], v[84:85]
	v_pk_fma_f32 v[72:73], v[44:45], v[120:121], v[72:73]
	v_pk_fma_f32 v[84:85], v[44:45], v[194:195], v[84:85]
	v_add_f32_e32 v82, v72, v73
	v_add_f32_e32 v201, v84, v85
	ds_read_b128 v[156:159], v65 offset:18432
	v_pk_mul_f32 v[74:75], v[46:47], v[122:123]
	v_add_f32_dpp v82, v82, v82 quad_perm:[1,0,3,2] row_mask:0xf bank_mask:0xf bound_ctrl:1
	ds_read_b128 v[160:163], v65 offset:18560
	v_pk_mul_f32 v[76:77], v[48:49], v[124:125]
	v_add_f32_dpp v82, v82, v82 quad_perm:[2,3,0,1] row_mask:0xf bank_mask:0xf bound_ctrl:1
	ds_read_b128 v[164:167], v65 offset:18688
	v_pk_mul_f32 v[78:79], v[42:43], v[126:127]
	v_add_f32_dpp v82, v82, v82 row_half_mirror row_mask:0xf bank_mask:0xf bound_ctrl:1
	v_pk_mul_f32 v[80:81], v[44:45], v[128:129]
	ds_read_b128 v[168:171], v65 offset:18816
	v_pk_fma_f32 v[74:75], v[198:199], v[108:109], v[74:75] op_sel_hi:[0,1,1]
	ds_read_b128 v[172:175], v65 offset:19200
	v_pk_fma_f32 v[76:77], v[198:199], v[110:111], v[76:77] op_sel_hi:[0,1,1]
	ds_read_b128 v[176:179], v65 offset:19328
	v_pk_fma_f32 v[78:79], v[198:199], v[88:89], v[78:79] op_sel_hi:[0,1,1]
	ds_read_b32 v196, v66 offset:19712
	v_pk_fma_f32 v[80:81], v[198:199], v[90:91], v[80:81] op_sel_hi:[0,1,1]
	ds_read_b128 v[180:183], v65 offset:18944
	v_pk_fma_f32 v[46:47], v[92:93], v[82:83], v[74:75] op_sel_hi:[1,0,1]
	ds_read_b128 v[184:187], v65 offset:19072
	v_pk_fma_f32 v[48:49], v[94:95], v[82:83], v[76:77] op_sel_hi:[1,0,1]
	ds_read_b128 v[188:191], v65 offset:19456
	v_pk_fma_f32 v[42:43], v[96:97], v[82:83], v[78:79] op_sel_hi:[1,0,1]
	ds_read_b128 v[192:195], v65 offset:19584
	v_pk_fma_f32 v[44:45], v[98:99], v[82:83], v[80:81] op_sel_hi:[1,0,1]
	s_waitcnt lgkmcnt(2)
	v_pk_mul_f32 v[72:73], v[46:47], v[156:157]
	v_pk_mul_f32 v[84:85], v[46:47], v[100:101]
	v_pk_fma_f32 v[72:73], v[48:49], v[158:159], v[72:73]
	v_pk_fma_f32 v[84:85], v[48:49], v[102:103], v[84:85]
	v_pk_fma_f32 v[72:73], v[42:43], v[160:161], v[72:73]
	v_pk_fma_f32 v[84:85], v[42:43], v[68:69], v[84:85]
	v_pk_fma_f32 v[72:73], v[44:45], v[162:163], v[72:73]
	v_pk_fma_f32 v[84:85], v[44:45], v[70:71], v[84:85]
	v_add_f32_e32 v82, v72, v73
	v_add_f32_e32 v202, v84, v85
	ds_read_b128 v[114:117], v65 offset:19968
	v_pk_mul_f32 v[74:75], v[46:47], v[164:165]
	v_add_f32_dpp v82, v82, v82 quad_perm:[1,0,3,2] row_mask:0xf bank_mask:0xf bound_ctrl:1
	ds_read_b128 v[118:121], v65 offset:20096
	v_pk_mul_f32 v[76:77], v[48:49], v[166:167]
	v_add_f32_dpp v82, v82, v82 quad_perm:[2,3,0,1] row_mask:0xf bank_mask:0xf bound_ctrl:1
	ds_read_b128 v[122:125], v65 offset:20224
	v_pk_mul_f32 v[78:79], v[42:43], v[168:169]
	v_add_f32_dpp v82, v82, v82 row_half_mirror row_mask:0xf bank_mask:0xf bound_ctrl:1
	v_pk_mul_f32 v[80:81], v[44:45], v[170:171]
	ds_read_b128 v[126:129], v65 offset:20352
	v_pk_fma_f32 v[74:75], v[196:197], v[172:173], v[74:75] op_sel_hi:[0,1,1]
	ds_read_b128 v[108:111], v65 offset:20736
	v_pk_fma_f32 v[76:77], v[196:197], v[174:175], v[76:77] op_sel_hi:[0,1,1]
	ds_read_b128 v[88:91], v65 offset:20864
	v_pk_fma_f32 v[78:79], v[196:197], v[176:177], v[78:79] op_sel_hi:[0,1,1]
	ds_read_b32 v198, v66 offset:21248
	v_pk_fma_f32 v[80:81], v[196:197], v[178:179], v[80:81] op_sel_hi:[0,1,1]
	ds_read_b128 v[92:95], v65 offset:20480
	v_pk_fma_f32 v[46:47], v[180:181], v[82:83], v[74:75] op_sel_hi:[1,0,1]
	ds_read_b128 v[96:99], v65 offset:20608
	v_pk_fma_f32 v[48:49], v[182:183], v[82:83], v[76:77] op_sel_hi:[1,0,1]
	ds_read_b128 v[100:103], v65 offset:20992
	v_pk_fma_f32 v[42:43], v[184:185], v[82:83], v[78:79] op_sel_hi:[1,0,1]
	ds_read_b128 v[68:71], v65 offset:21120
	v_pk_fma_f32 v[44:45], v[186:187], v[82:83], v[80:81] op_sel_hi:[1,0,1]
	s_waitcnt lgkmcnt(2)
	v_pk_mul_f32 v[72:73], v[46:47], v[114:115]
	v_pk_mul_f32 v[84:85], v[46:47], v[188:189]
	v_pk_fma_f32 v[72:73], v[48:49], v[116:117], v[72:73]
	v_pk_fma_f32 v[84:85], v[48:49], v[190:191], v[84:85]
	v_pk_fma_f32 v[72:73], v[42:43], v[118:119], v[72:73]
	v_pk_fma_f32 v[84:85], v[42:43], v[192:193], v[84:85]
	v_pk_fma_f32 v[72:73], v[44:45], v[120:121], v[72:73]
	v_pk_fma_f32 v[84:85], v[44:45], v[194:195], v[84:85]
	v_add_f32_e32 v82, v72, v73
	v_add_f32_e32 v203, v84, v85
	ds_read_b128 v[156:159], v65 offset:21504
	v_pk_mul_f32 v[74:75], v[46:47], v[122:123]
	v_add_f32_dpp v82, v82, v82 quad_perm:[1,0,3,2] row_mask:0xf bank_mask:0xf bound_ctrl:1
	ds_read_b128 v[160:163], v65 offset:21632
	v_pk_mul_f32 v[76:77], v[48:49], v[124:125]
	v_add_f32_dpp v82, v82, v82 quad_perm:[2,3,0,1] row_mask:0xf bank_mask:0xf bound_ctrl:1
	ds_read_b128 v[164:167], v65 offset:21760
	v_pk_mul_f32 v[78:79], v[42:43], v[126:127]
	v_add_f32_dpp v82, v82, v82 row_half_mirror row_mask:0xf bank_mask:0xf bound_ctrl:1
	v_pk_mul_f32 v[80:81], v[44:45], v[128:129]
	ds_read_b128 v[168:171], v65 offset:21888
	v_pk_fma_f32 v[74:75], v[198:199], v[108:109], v[74:75] op_sel_hi:[0,1,1]
	ds_read_b128 v[172:175], v65 offset:22272
	v_pk_fma_f32 v[76:77], v[198:199], v[110:111], v[76:77] op_sel_hi:[0,1,1]
	ds_read_b128 v[176:179], v65 offset:22400
	v_pk_fma_f32 v[78:79], v[198:199], v[88:89], v[78:79] op_sel_hi:[0,1,1]
	ds_read_b32 v196, v66 offset:22784
	v_pk_fma_f32 v[80:81], v[198:199], v[90:91], v[80:81] op_sel_hi:[0,1,1]
	ds_read_b128 v[180:183], v65 offset:22016
	v_pk_fma_f32 v[46:47], v[92:93], v[82:83], v[74:75] op_sel_hi:[1,0,1]
	ds_read_b128 v[184:187], v65 offset:22144
	v_pk_fma_f32 v[48:49], v[94:95], v[82:83], v[76:77] op_sel_hi:[1,0,1]
	ds_read_b128 v[188:191], v65 offset:22528
	v_pk_fma_f32 v[42:43], v[96:97], v[82:83], v[78:79] op_sel_hi:[1,0,1]
	ds_read_b128 v[192:195], v65 offset:22656
	v_pk_fma_f32 v[44:45], v[98:99], v[82:83], v[80:81] op_sel_hi:[1,0,1]
	s_waitcnt lgkmcnt(2)
	v_pk_mul_f32 v[72:73], v[46:47], v[156:157]
	v_pk_mul_f32 v[84:85], v[46:47], v[100:101]
	v_pk_fma_f32 v[72:73], v[48:49], v[158:159], v[72:73]
	v_pk_fma_f32 v[84:85], v[48:49], v[102:103], v[84:85]
	v_pk_fma_f32 v[72:73], v[42:43], v[160:161], v[72:73]
	v_pk_fma_f32 v[84:85], v[42:43], v[68:69], v[84:85]
	v_pk_fma_f32 v[72:73], v[44:45], v[162:163], v[72:73]
	v_pk_fma_f32 v[84:85], v[44:45], v[70:71], v[84:85]
	v_add_f32_e32 v82, v72, v73
	v_add_f32_e32 v210, v84, v85
	ds_read_b128 v[114:117], v65 offset:23040
	v_pk_mul_f32 v[74:75], v[46:47], v[164:165]
	v_add_f32_dpp v82, v82, v82 quad_perm:[1,0,3,2] row_mask:0xf bank_mask:0xf bound_ctrl:1
	ds_read_b128 v[118:121], v65 offset:23168
	v_pk_mul_f32 v[76:77], v[48:49], v[166:167]
	v_add_f32_dpp v82, v82, v82 quad_perm:[2,3,0,1] row_mask:0xf bank_mask:0xf bound_ctrl:1
	ds_read_b128 v[122:125], v65 offset:23296
	v_pk_mul_f32 v[78:79], v[42:43], v[168:169]
	v_add_f32_dpp v82, v82, v82 row_half_mirror row_mask:0xf bank_mask:0xf bound_ctrl:1
	v_pk_mul_f32 v[80:81], v[44:45], v[170:171]
	ds_read_b128 v[126:129], v65 offset:23424
	v_pk_fma_f32 v[74:75], v[196:197], v[172:173], v[74:75] op_sel_hi:[0,1,1]
	ds_read_b128 v[108:111], v65 offset:23808
	v_pk_fma_f32 v[76:77], v[196:197], v[174:175], v[76:77] op_sel_hi:[0,1,1]
	ds_read_b128 v[88:91], v65 offset:23936
	v_pk_fma_f32 v[78:79], v[196:197], v[176:177], v[78:79] op_sel_hi:[0,1,1]
	ds_read_b32 v198, v66 offset:24320
	v_pk_fma_f32 v[80:81], v[196:197], v[178:179], v[80:81] op_sel_hi:[0,1,1]
	ds_read_b128 v[92:95], v65 offset:23552
	v_pk_fma_f32 v[46:47], v[180:181], v[82:83], v[74:75] op_sel_hi:[1,0,1]
	ds_read_b128 v[96:99], v65 offset:23680
	v_pk_fma_f32 v[48:49], v[182:183], v[82:83], v[76:77] op_sel_hi:[1,0,1]
	ds_read_b128 v[100:103], v65 offset:24064
	v_pk_fma_f32 v[42:43], v[184:185], v[82:83], v[78:79] op_sel_hi:[1,0,1]
	ds_read_b128 v[68:71], v65 offset:24192
	v_pk_fma_f32 v[44:45], v[186:187], v[82:83], v[80:81] op_sel_hi:[1,0,1]
	s_waitcnt lgkmcnt(2)
	v_pk_mul_f32 v[72:73], v[46:47], v[114:115]
	v_pk_mul_f32 v[84:85], v[46:47], v[188:189]
	v_pk_fma_f32 v[72:73], v[48:49], v[116:117], v[72:73]
	v_pk_fma_f32 v[84:85], v[48:49], v[190:191], v[84:85]
	v_pk_fma_f32 v[72:73], v[42:43], v[118:119], v[72:73]
	v_pk_fma_f32 v[84:85], v[42:43], v[192:193], v[84:85]
	v_pk_fma_f32 v[72:73], v[44:45], v[120:121], v[72:73]
	v_pk_fma_f32 v[84:85], v[44:45], v[194:195], v[84:85]
	v_add_f32_e32 v82, v72, v73
	v_add_f32_e32 v211, v84, v85
	v_pk_mul_f32 v[74:75], v[46:47], v[122:123]
	v_add_f32_dpp v82, v82, v82 quad_perm:[1,0,3,2] row_mask:0xf bank_mask:0xf bound_ctrl:1
	v_pk_mul_f32 v[76:77], v[48:49], v[124:125]
	v_pk_mul_f32 v[78:79], v[42:43], v[126:127]
	v_add_f32_dpp v82, v82, v82 quad_perm:[2,3,0,1] row_mask:0xf bank_mask:0xf bound_ctrl:1
	v_pk_mul_f32 v[80:81], v[44:45], v[128:129]
	v_pk_fma_f32 v[74:75], v[198:199], v[108:109], v[74:75] op_sel_hi:[0,1,1]
	v_add_f32_dpp v82, v82, v82 row_half_mirror row_mask:0xf bank_mask:0xf bound_ctrl:1
	v_pk_fma_f32 v[76:77], v[198:199], v[110:111], v[76:77] op_sel_hi:[0,1,1]
	v_pk_fma_f32 v[78:79], v[198:199], v[88:89], v[78:79] op_sel_hi:[0,1,1]
	v_pk_fma_f32 v[80:81], v[198:199], v[90:91], v[80:81] op_sel_hi:[0,1,1]
	v_pk_fma_f32 v[46:47], v[92:93], v[82:83], v[74:75] op_sel_hi:[1,0,1]
	v_pk_fma_f32 v[48:49], v[94:95], v[82:83], v[76:77] op_sel_hi:[1,0,1]
	v_pk_fma_f32 v[42:43], v[96:97], v[82:83], v[78:79] op_sel_hi:[1,0,1]
	v_pk_fma_f32 v[44:45], v[98:99], v[82:83], v[80:81] op_sel_hi:[1,0,1]
	s_waitcnt lgkmcnt(0)
	v_pk_mul_f32 v[84:85], v[46:47], v[100:101]
	s_mov_b32 s6, 0xcccccccc
	v_pk_fma_f32 v[84:85], v[48:49], v[102:103], v[84:85]
	s_mov_b32 s7, 0xcccccccc
	v_pk_fma_f32 v[84:85], v[42:43], v[68:69], v[84:85]
	s_mov_b32 s12, 0xaaaaaaaa
	v_pk_fma_f32 v[84:85], v[44:45], v[70:71], v[84:85]
	s_mov_b32 s13, 0xaaaaaaaa
	v_add_f32_e32 v212, v84, v85
	v_add_f32_dpp v83, v83, v83 row_shl:4 row_mask:0xf bank_mask:0x5
	v_add_f32_dpp v87, v87, v87 row_shl:4 row_mask:0xf bank_mask:0x5
	v_add_f32_dpp v104, v104, v104 row_shl:4 row_mask:0xf bank_mask:0x5
	v_add_f32_dpp v105, v105, v105 row_shl:4 row_mask:0xf bank_mask:0x5
	v_add_f32_dpp v83, v67, v67 row_shr:4 row_mask:0xf bank_mask:0xa
	v_add_f32_dpp v87, v60, v60 row_shr:4 row_mask:0xf bank_mask:0xa
	v_add_f32_dpp v104, v62, v62 row_shr:4 row_mask:0xf bank_mask:0xa
	v_add_f32_dpp v105, v197, v197 row_shr:4 row_mask:0xf bank_mask:0xa
	v_add_f32_dpp v199, v199, v199 row_shl:4 row_mask:0xf bank_mask:0x5
	v_add_f32_dpp v200, v200, v200 row_shl:4 row_mask:0xf bank_mask:0x5
	v_add_f32_dpp v201, v201, v201 row_shl:4 row_mask:0xf bank_mask:0x5
	v_add_f32_dpp v202, v202, v202 row_shl:4 row_mask:0xf bank_mask:0x5
	v_add_f32_dpp v199, v203, v203 row_shr:4 row_mask:0xf bank_mask:0xa
	v_add_f32_dpp v200, v210, v210 row_shr:4 row_mask:0xf bank_mask:0xa
	v_add_f32_dpp v201, v211, v211 row_shr:4 row_mask:0xf bank_mask:0xa
	v_add_f32_dpp v202, v212, v212 row_shr:4 row_mask:0xf bank_mask:0xa
	v_add_f32_dpp v67, v83, v83 quad_perm:[2,3,0,1] row_mask:0xf bank_mask:0xf
	v_add_f32_dpp v60, v87, v87 quad_perm:[2,3,0,1] row_mask:0xf bank_mask:0xf
	v_add_f32_dpp v62, v104, v104 quad_perm:[2,3,0,1] row_mask:0xf bank_mask:0xf
	v_add_f32_dpp v197, v105, v105 quad_perm:[2,3,0,1] row_mask:0xf bank_mask:0xf
	v_cndmask_b32_e64 v83, v67, v62, s[6:7]
	v_cndmask_b32_e64 v87, v60, v197, s[6:7]
	s_nop 0
	v_add_f32_dpp v104, v83, v83 quad_perm:[1,0,3,2] row_mask:0xf bank_mask:0xf
	v_add_f32_dpp v105, v87, v87 quad_perm:[1,0,3,2] row_mask:0xf bank_mask:0xf
	v_cndmask_b32_e64 v213, v104, v105, s[12:13]
	v_add_f32_dpp v203, v199, v199 quad_perm:[2,3,0,1] row_mask:0xf bank_mask:0xf
	v_add_f32_dpp v210, v200, v200 quad_perm:[2,3,0,1] row_mask:0xf bank_mask:0xf
	v_add_f32_dpp v211, v201, v201 quad_perm:[2,3,0,1] row_mask:0xf bank_mask:0xf
	v_add_f32_dpp v212, v202, v202 quad_perm:[2,3,0,1] row_mask:0xf bank_mask:0xf
	v_cndmask_b32_e64 v199, v203, v211, s[6:7]
	v_cndmask_b32_e64 v200, v210, v212, s[6:7]
	s_nop 0
	v_add_f32_dpp v201, v199, v199 quad_perm:[1,0,3,2] row_mask:0xf bank_mask:0xf
	v_add_f32_dpp v202, v200, v200 quad_perm:[1,0,3,2] row_mask:0xf bank_mask:0xf
	v_cndmask_b32_e64 v214, v201, v202, s[12:13]
	s_lshl_b32 s46, s42, 4
	v_or_b32_e32 v61, s46, v64
	v_sub_u32_e32 v62, 0xff, v61
	v_cndmask_b32_e64 v62, v62, v61, s[0:1]
	v_lshlrev_b32_e32 v106, 10, v62
	v_lshl_add_u64 v[88:89], v[58:59], 0, v[106:107]
	global_store_dword v[88:89], v213, off
	v_or_b32_e32 v62, 8, v61
	v_sub_u32_e32 v85, 0xf7, v61
	v_cndmask_b32_e64 v62, v85, v62, s[0:1]
	v_lshlrev_b32_e32 v106, 10, v62
	v_lshl_add_u64 v[88:89], v[58:59], 0, v[106:107]
	global_store_dword v[88:89], v214, off
	s_waitcnt vmcnt(4)
	v_lshlrev_b32_e32 v88, 16, v26
	v_and_b32_e32 v89, 0xffff0000, v26
	v_lshlrev_b32_e32 v90, 16, v27
	v_and_b32_e32 v91, 0xffff0000, v27
	s_waitcnt vmcnt(8)
	ds_write_b128 v56, v[2:5] offset:24576
	s_waitcnt vmcnt(7)
	ds_write_b128 v56, v[6:9] offset:30720
	ds_write_b128 v56, v[10:13] offset:36864
	ds_write_b128 v56, v[18:21] offset:43008
	ds_write_b128 v57, v[88:91] offset:25600
	v_lshlrev_b32_e32 v88, 16, v28
	v_and_b32_e32 v89, 0xffff0000, v28
	v_lshlrev_b32_e32 v90, 16, v29
	v_and_b32_e32 v91, 0xffff0000, v29
	s_cmp_gt_u32 s42, 12
	ds_write_b128 v57, v[88:91] offset:25616
	s_cbranch_scc1 .LBB0_1226
	s_add_i32 s12, s46, 48
	s_sub_i32 s13, 0xff, s12
	s_add_i32 s13, s13, s2
	s_add_i32 s12, s12, s2
	s_cmp_lg_u64 s[0:1], 0
	s_cselect_b32 s12, s12, s13
	s_ashr_i32 vcc_hi, s12, 31
	s_mov_b32 vcc_lo, s12
	s_lshl_b64 vcc, vcc, 10
	v_lshl_add_u64 v[2:3], v[216:217], 0, vcc
	v_lshl_add_u64 v[6:7], v[218:219], 0, vcc
	v_lshl_add_u64 v[10:11], v[220:221], 0, vcc
	v_lshl_add_u64 v[18:19], v[222:223], 0, vcc
	s_mul_hi_i32 s13, s12, s37
	s_mul_i32 s12, s12, s37
	v_lshl_add_u64 v[26:27], v[224:225], 0, s[12:13]
	global_load_dwordx4 v[2:5], v[2:3], off
	global_load_dwordx4 v[6:9], v[6:7], off
	global_load_dwordx4 v[10:13], v[10:11], off
	global_load_dwordx4 v[18:21], v[18:19], off
	global_load_dwordx4 v[26:29], v[26:27], off

.LBB0_1230:
	s_cmp_gt_u32 s42, 11
	s_cbranch_scc1 .LBB0_1221
	s_add_i32 s46, s46, 64
	s_waitcnt vmcnt(4)
	s_mov_b32 s12, s46
	s_sub_i32 s13, 0xff, s12
	s_add_i32 s13, s13, s2
	s_add_i32 s12, s12, s2
	s_cmp_lg_u64 s[0:1], 0
	s_cselect_b32 s12, s12, s13
	s_ashr_i32 vcc_hi, s12, 31
	s_mov_b32 vcc_lo, s12
	s_lshl_b64 vcc, vcc, 10
	v_lshl_add_u64 v[14:15], v[216:217], 0, vcc
	v_lshl_add_u64 v[22:23], v[218:219], 0, vcc
	v_lshl_add_u64 v[30:31], v[220:221], 0, vcc
	v_lshl_add_u64 v[34:35], v[222:223], 0, vcc
	s_mul_hi_i32 s13, s12, s37
	s_mul_i32 s12, s12, s37
	v_lshl_add_u64 v[38:39], v[224:225], 0, s[12:13]
	global_load_dwordx4 v[14:17], v[14:15], off
	global_load_dwordx4 v[22:25], v[22:23], off
	global_load_dwordx4 v[30:33], v[30:31], off
	global_load_dwordx4 v[34:37], v[34:35], off
	global_load_dwordx4 v[38:41], v[38:39], off
	s_branch .LBB0_1221
